# static priority raise on the other half: flips removed, waves 0-3 run the GEMM K-loops at user priority 1
# speedup vs baseline: 1.0104x; 1.0002x over previous
; #define PG8_BAR __builtin_amdgcn_s_barrier()
; template <class Sched, class Epi, bool ALIGN_EPI, bool SP2>
; __device__ __forceinline__ void gemm_phase(LAS unsigned char* lds, const int K, const int lda, const int ldb, const Sched& S, const Epi& E) {
;     ...
;     for (;;) {
;         const bool has_next = S.next(ui + 1, nxt);
;         const char* nA = has_next ? nxt.A : cA; const char* nB = has_next ? nxt.B : cB;
;         for (int t = 0; t < nt; t += 2) {
;     ...
;         if (!keep) {
; #pragma unroll
;         for (int a = 0; a < 2; ++a)
; #pragma unroll
;             for (int b = 0; b < 2; ++b)
; #pragma unroll
;                 for (int m = 0; m < 4; ++m)
; #pragma unroll
;                     for (int n = 0; n < 2; ++n) acc[a][b][m][n] = (f32x4){0.f, 0.f, 0.f, 0.f};
;         }
;         cur = nxt; cA = nA; cB = nB; ++ui;
;         if constexpr (ALIGN_EPI) { if (wr == 1) PG8_BAR; }
.LBB0_154:
	s_add_u32 s20, s20, 0x80080
	s_addc_u32 s21, s21, 0
	s_add_u32 s13, s22, 0x100
	v_mov_b32_e32 v0, 0
	s_addc_u32 s74, s23, 0
	s_mov_b32 s75, -2
	v_mov_b32_e32 v1, v0
	v_mov_b32_e32 v2, v0
	v_mov_b32_e32 v3, v0
	v_mov_b32_e32 v4, v0
	v_mov_b32_e32 v5, v0
	v_mov_b32_e32 v6, v0
	v_mov_b32_e32 v7, v0
	v_mov_b32_e32 v16, v0
	v_mov_b32_e32 v17, v0
	v_mov_b32_e32 v18, v0
	v_mov_b32_e32 v19, v0
	v_mov_b32_e32 v20, v0
	v_mov_b32_e32 v21, v0
	v_mov_b32_e32 v22, v0
	v_mov_b32_e32 v23, v0
	v_mov_b32_e32 v32, v0
	v_mov_b32_e32 v33, v0
	v_mov_b32_e32 v34, v0
	v_mov_b32_e32 v35, v0
	v_mov_b32_e32 v36, v0
	v_mov_b32_e32 v37, v0
	v_mov_b32_e32 v38, v0
	v_mov_b32_e32 v39, v0
	v_mov_b32_e32 v48, v0
	v_mov_b32_e32 v49, v0
	v_mov_b32_e32 v50, v0
	v_mov_b32_e32 v51, v0
	v_mov_b32_e32 v52, v0
	v_mov_b32_e32 v53, v0
	v_mov_b32_e32 v54, v0
	v_mov_b32_e32 v55, v0
	v_mov_b32_e32 v8, v0
	v_mov_b32_e32 v9, v0
	v_mov_b32_e32 v10, v0
	v_mov_b32_e32 v11, v0
	v_mov_b32_e32 v12, v0
	v_mov_b32_e32 v13, v0
	v_mov_b32_e32 v14, v0
	v_mov_b32_e32 v15, v0
	v_mov_b32_e32 v24, v0
	v_mov_b32_e32 v25, v0
	v_mov_b32_e32 v26, v0
	v_mov_b32_e32 v27, v0
	v_mov_b32_e32 v28, v0
	v_mov_b32_e32 v29, v0
	v_mov_b32_e32 v30, v0
	v_mov_b32_e32 v31, v0
	v_mov_b32_e32 v40, v0
	v_mov_b32_e32 v41, v0
	v_mov_b32_e32 v42, v0
	v_mov_b32_e32 v43, v0
	v_mov_b32_e32 v44, v0
	v_mov_b32_e32 v45, v0
	v_mov_b32_e32 v46, v0
	v_mov_b32_e32 v47, v0
	v_mov_b32_e32 v56, v0
	v_mov_b32_e32 v57, v0
	v_mov_b32_e32 v58, v0
	v_mov_b32_e32 v59, v0
	v_mov_b32_e32 v60, v0
	v_mov_b32_e32 v61, v0
	v_mov_b32_e32 v62, v0
	v_mov_b32_e32 v63, v0
	v_mov_b32_e32 v64, v0
	v_mov_b32_e32 v65, v0
	v_mov_b32_e32 v66, v0
	v_mov_b32_e32 v67, v0
	v_mov_b32_e32 v68, v0
	v_mov_b32_e32 v69, v0
	v_mov_b32_e32 v70, v0
	v_mov_b32_e32 v71, v0
	v_mov_b32_e32 v80, v0
	v_mov_b32_e32 v81, v0
	v_mov_b32_e32 v82, v0
	v_mov_b32_e32 v83, v0
	v_mov_b32_e32 v84, v0
	v_mov_b32_e32 v85, v0
	v_mov_b32_e32 v86, v0
	v_mov_b32_e32 v87, v0
	v_mov_b32_e32 v96, v0
	v_mov_b32_e32 v97, v0
	v_mov_b32_e32 v98, v0
	v_mov_b32_e32 v99, v0
	v_mov_b32_e32 v100, v0
	v_mov_b32_e32 v101, v0
	v_mov_b32_e32 v102, v0
	v_mov_b32_e32 v103, v0
	v_mov_b32_e32 v112, v0
	v_mov_b32_e32 v113, v0
	v_mov_b32_e32 v114, v0
	v_mov_b32_e32 v115, v0
	v_mov_b32_e32 v116, v0
	v_mov_b32_e32 v117, v0
	v_mov_b32_e32 v118, v0
	v_mov_b32_e32 v119, v0
	v_mov_b32_e32 v72, v0
	v_mov_b32_e32 v73, v0
	v_mov_b32_e32 v74, v0
	v_mov_b32_e32 v75, v0
	v_mov_b32_e32 v76, v0
	v_mov_b32_e32 v77, v0
	v_mov_b32_e32 v78, v0
	v_mov_b32_e32 v79, v0
	v_mov_b32_e32 v88, v0
	v_mov_b32_e32 v89, v0
	v_mov_b32_e32 v90, v0
	v_mov_b32_e32 v91, v0
	v_mov_b32_e32 v92, v0
	v_mov_b32_e32 v93, v0
	v_mov_b32_e32 v94, v0
	v_mov_b32_e32 v95, v0
	v_mov_b32_e32 v104, v0
	v_mov_b32_e32 v105, v0
	v_mov_b32_e32 v106, v0
	v_mov_b32_e32 v107, v0
	v_mov_b32_e32 v108, v0
	v_mov_b32_e32 v109, v0
	v_mov_b32_e32 v110, v0
	v_mov_b32_e32 v111, v0
	v_mov_b32_e32 v120, v0
	v_mov_b32_e32 v121, v0
	v_mov_b32_e32 v122, v0
	v_mov_b32_e32 v123, v0
	v_mov_b32_e32 v124, v0
	v_mov_b32_e32 v125, v0
	v_mov_b32_e32 v126, v0
	v_mov_b32_e32 v127, v0
	v_readlane_b32 s98, v255, 13
	s_nop 4
	s_cmp_gt_u32 s98, 3
	s_cbranch_scc1 .Lprio_skip_155
	s_setprio 1

; #define PG8_BAR __builtin_amdgcn_s_barrier()
; template <class Sched, class Epi, bool ALIGN_EPI, bool SP2>
; __device__ __forceinline__ void gemm_phase(LAS unsigned char* lds, const int K, const int lda, const int ldb, const Sched& S, const Epi& E) {
;     ...
;     for (;;) {
;         const bool has_next = S.next(ui + 1, nxt);
;         const char* nA = has_next ? nxt.A : cA; const char* nB = has_next ? nxt.B : cB;
;         for (int t = 0; t < nt; t += 2) {
;     ...
;         if (!keep) {
; #pragma unroll
;         for (int a = 0; a < 2; ++a)
; #pragma unroll
;             for (int b = 0; b < 2; ++b)
; #pragma unroll
;                 for (int m = 0; m < 4; ++m)
; #pragma unroll
;                     for (int n = 0; n < 2; ++n) acc[a][b][m][n] = (f32x4){0.f, 0.f, 0.f, 0.f};
;         }
;         cur = nxt; cA = nA; cB = nB; ++ui;
;         if constexpr (ALIGN_EPI) { if (wr == 1) PG8_BAR; }
.LBB0_242:
	s_add_u32 s89, s22, 0x100
	v_mov_b32_e32 v0, 0
	s_addc_u32 s90, s23, 0
	s_mov_b32 s91, -2
	v_mov_b32_e32 v1, v0
	s_waitcnt lgkmcnt(0)
	v_mov_b32_e32 v2, v0
	v_mov_b32_e32 v3, v0
	v_mov_b32_e32 v4, v0
	v_mov_b32_e32 v5, v0
	v_mov_b32_e32 v6, v0
	v_mov_b32_e32 v7, v0
	v_mov_b32_e32 v16, v0
	v_mov_b32_e32 v17, v0
	v_mov_b32_e32 v18, v0
	v_mov_b32_e32 v19, v0
	v_mov_b32_e32 v20, v0
	v_mov_b32_e32 v21, v0
	v_mov_b32_e32 v22, v0
	v_mov_b32_e32 v23, v0
	v_mov_b32_e32 v32, v0
	v_mov_b32_e32 v33, v0
	v_mov_b32_e32 v34, v0
	v_mov_b32_e32 v35, v0
	v_mov_b32_e32 v36, v0
	v_mov_b32_e32 v37, v0
	v_mov_b32_e32 v38, v0
	v_mov_b32_e32 v39, v0
	v_mov_b32_e32 v48, v0
	v_mov_b32_e32 v49, v0
	v_mov_b32_e32 v50, v0
	v_mov_b32_e32 v51, v0
	v_mov_b32_e32 v52, v0
	v_mov_b32_e32 v53, v0
	v_mov_b32_e32 v54, v0
	v_mov_b32_e32 v55, v0
	v_mov_b32_e32 v8, v0
	v_mov_b32_e32 v9, v0
	v_mov_b32_e32 v10, v0
	v_mov_b32_e32 v11, v0
	v_mov_b32_e32 v12, v0
	v_mov_b32_e32 v13, v0
	v_mov_b32_e32 v14, v0
	v_mov_b32_e32 v15, v0
	v_mov_b32_e32 v24, v0
	v_mov_b32_e32 v25, v0
	v_mov_b32_e32 v26, v0
	v_mov_b32_e32 v27, v0
	v_mov_b32_e32 v28, v0
	v_mov_b32_e32 v29, v0
	v_mov_b32_e32 v30, v0
	v_mov_b32_e32 v31, v0
	v_mov_b32_e32 v40, v0
	v_mov_b32_e32 v41, v0
	v_mov_b32_e32 v42, v0
	v_mov_b32_e32 v43, v0
	v_mov_b32_e32 v44, v0
	v_mov_b32_e32 v45, v0
	v_mov_b32_e32 v46, v0
	v_mov_b32_e32 v47, v0
	v_mov_b32_e32 v56, v0
	v_mov_b32_e32 v57, v0
	v_mov_b32_e32 v58, v0
	v_mov_b32_e32 v59, v0
	v_mov_b32_e32 v60, v0
	v_mov_b32_e32 v61, v0
	v_mov_b32_e32 v62, v0
	v_mov_b32_e32 v63, v0
	v_mov_b32_e32 v64, v0
	v_mov_b32_e32 v65, v0
	v_mov_b32_e32 v66, v0
	v_mov_b32_e32 v67, v0
	v_mov_b32_e32 v68, v0
	v_mov_b32_e32 v69, v0
	v_mov_b32_e32 v70, v0
	v_mov_b32_e32 v71, v0
	v_mov_b32_e32 v80, v0
	v_mov_b32_e32 v81, v0
	v_mov_b32_e32 v82, v0
	v_mov_b32_e32 v83, v0
	v_mov_b32_e32 v84, v0
	v_mov_b32_e32 v85, v0
	v_mov_b32_e32 v86, v0
	v_mov_b32_e32 v87, v0
	v_mov_b32_e32 v96, v0
	v_mov_b32_e32 v97, v0
	v_mov_b32_e32 v98, v0
	v_mov_b32_e32 v99, v0
	v_mov_b32_e32 v100, v0
	v_mov_b32_e32 v101, v0
	v_mov_b32_e32 v102, v0
	v_mov_b32_e32 v103, v0
	v_mov_b32_e32 v112, v0
	v_mov_b32_e32 v113, v0
	v_mov_b32_e32 v114, v0
	v_mov_b32_e32 v115, v0
	v_mov_b32_e32 v116, v0
	v_mov_b32_e32 v117, v0
	v_mov_b32_e32 v118, v0
	v_mov_b32_e32 v119, v0
	v_mov_b32_e32 v72, v0
	v_mov_b32_e32 v73, v0
	v_mov_b32_e32 v74, v0
	v_mov_b32_e32 v75, v0
	v_mov_b32_e32 v76, v0
	v_mov_b32_e32 v77, v0
	v_mov_b32_e32 v78, v0
	v_mov_b32_e32 v79, v0
	v_mov_b32_e32 v88, v0
	v_mov_b32_e32 v89, v0
	v_mov_b32_e32 v90, v0
	v_mov_b32_e32 v91, v0
	v_mov_b32_e32 v92, v0
	v_mov_b32_e32 v93, v0
	v_mov_b32_e32 v94, v0
	v_mov_b32_e32 v95, v0
	v_mov_b32_e32 v104, v0
	v_mov_b32_e32 v105, v0
	v_mov_b32_e32 v106, v0
	v_mov_b32_e32 v107, v0
	v_mov_b32_e32 v108, v0
	v_mov_b32_e32 v109, v0
	v_mov_b32_e32 v110, v0
	v_mov_b32_e32 v111, v0
	v_mov_b32_e32 v120, v0
	v_mov_b32_e32 v121, v0
	v_mov_b32_e32 v122, v0
	v_mov_b32_e32 v123, v0
	v_mov_b32_e32 v128, v0
	v_mov_b32_e32 v129, v0
	v_mov_b32_e32 v130, v0
	v_mov_b32_e32 v131, v0
	v_readlane_b32 s98, v255, 13
	s_nop 4
	s_cmp_gt_u32 s98, 3
	s_cbranch_scc1 .Lprio_skip_243
	s_setprio 1

; #define PG8_BAR __builtin_amdgcn_s_barrier()
; template <class Sched, class Epi, bool ALIGN_EPI, bool SP2>
; __device__ __forceinline__ void gemm_phase(LAS unsigned char* lds, const int K, const int lda, const int ldb, const Sched& S, const Epi& E) {
;     ...
;     for (;;) {
;         const bool has_next = S.next(ui + 1, nxt);
;         const char* nA = has_next ? nxt.A : cA; const char* nB = has_next ? nxt.B : cB;
;         for (int t = 0; t < nt; t += 2) {
;     ...
;         if (!keep) {
; #pragma unroll
;         for (int a = 0; a < 2; ++a)
; #pragma unroll
;             for (int b = 0; b < 2; ++b)
; #pragma unroll
;                 for (int m = 0; m < 4; ++m)
; #pragma unroll
;                     for (int n = 0; n < 2; ++n) acc[a][b][m][n] = (f32x4){0.f, 0.f, 0.f, 0.f};
;         }
;         cur = nxt; cA = nA; cB = nB; ++ui;
;         if constexpr (ALIGN_EPI) { if (wr == 1) PG8_BAR; }
.LBB0_352:
	s_and_b64 s[6:7], s[24:25], exec
	s_cselect_b32 s1, s19, s27
	s_cselect_b32 s4, s18, s26
	s_cselect_b32 s21, s23, s29
	s_cselect_b32 vcc_lo, s22, s28
	s_add_u32 s26, s26, 0x80080
	s_addc_u32 s27, s27, 0
	s_add_u32 vcc_hi, s28, 0x100
	v_mov_b32_e32 v0, 0
	s_addc_u32 s6, s29, 0
	s_mov_b32 s7, -2
	v_mov_b32_e32 v1, v0
	v_mov_b32_e32 v2, v0
	v_mov_b32_e32 v3, v0
	v_mov_b32_e32 v4, v0
	v_mov_b32_e32 v5, v0
	v_mov_b32_e32 v6, v0
	v_mov_b32_e32 v7, v0
	v_mov_b32_e32 v16, v0
	v_mov_b32_e32 v17, v0
	v_mov_b32_e32 v18, v0
	v_mov_b32_e32 v19, v0
	v_mov_b32_e32 v20, v0
	v_mov_b32_e32 v21, v0
	v_mov_b32_e32 v22, v0
	v_mov_b32_e32 v23, v0
	v_mov_b32_e32 v40, v0
	v_mov_b32_e32 v41, v0
	v_mov_b32_e32 v42, v0
	v_mov_b32_e32 v43, v0
	v_mov_b32_e32 v44, v0
	v_mov_b32_e32 v45, v0
	v_mov_b32_e32 v46, v0
	v_mov_b32_e32 v47, v0
	v_mov_b32_e32 v96, v0
	v_mov_b32_e32 v97, v0
	v_mov_b32_e32 v98, v0
	v_mov_b32_e32 v99, v0
	v_mov_b32_e32 v100, v0
	v_mov_b32_e32 v101, v0
	v_mov_b32_e32 v102, v0
	v_mov_b32_e32 v103, v0
	v_mov_b32_e32 v8, v0
	v_mov_b32_e32 v9, v0
	v_mov_b32_e32 v10, v0
	v_mov_b32_e32 v11, v0
	v_mov_b32_e32 v12, v0
	v_mov_b32_e32 v13, v0
	v_mov_b32_e32 v14, v0
	v_mov_b32_e32 v15, v0
	v_mov_b32_e32 v24, v0
	v_mov_b32_e32 v25, v0
	v_mov_b32_e32 v26, v0
	v_mov_b32_e32 v27, v0
	v_mov_b32_e32 v28, v0
	v_mov_b32_e32 v29, v0
	v_mov_b32_e32 v30, v0
	v_mov_b32_e32 v31, v0
	v_mov_b32_e32 v72, v0
	v_mov_b32_e32 v73, v0
	v_mov_b32_e32 v74, v0
	v_mov_b32_e32 v75, v0
	v_mov_b32_e32 v84, v0
	v_mov_b32_e32 v85, v0
	v_mov_b32_e32 v86, v0
	v_mov_b32_e32 v87, v0
	v_mov_b32_e32 v104, v0
	v_mov_b32_e32 v105, v0
	v_mov_b32_e32 v106, v0
	v_mov_b32_e32 v107, v0
	v_mov_b32_e32 v108, v0
	v_mov_b32_e32 v109, v0
	v_mov_b32_e32 v110, v0
	v_mov_b32_e32 v111, v0
	v_mov_b32_e32 v112, v0
	v_mov_b32_e32 v113, v0
	v_mov_b32_e32 v114, v0
	v_mov_b32_e32 v115, v0
	v_mov_b32_e32 v116, v0
	v_mov_b32_e32 v117, v0
	v_mov_b32_e32 v118, v0
	v_mov_b32_e32 v119, v0
	v_mov_b32_e32 v128, v0
	v_mov_b32_e32 v129, v0
	v_mov_b32_e32 v130, v0
	v_mov_b32_e32 v131, v0
	v_mov_b32_e32 v132, v0
	v_mov_b32_e32 v133, v0
	v_mov_b32_e32 v134, v0
	v_mov_b32_e32 v135, v0
	v_mov_b32_e32 v144, v0
	v_mov_b32_e32 v145, v0
	v_mov_b32_e32 v146, v0
	v_mov_b32_e32 v147, v0
	v_mov_b32_e32 v148, v0
	v_mov_b32_e32 v149, v0
	v_mov_b32_e32 v150, v0
	v_mov_b32_e32 v151, v0
	v_mov_b32_e32 v160, v0
	v_mov_b32_e32 v161, v0
	v_mov_b32_e32 v162, v0
	v_mov_b32_e32 v163, v0
	v_mov_b32_e32 v164, v0
	v_mov_b32_e32 v165, v0
	v_mov_b32_e32 v166, v0
	v_mov_b32_e32 v167, v0
	v_mov_b32_e32 v120, v0
	v_mov_b32_e32 v121, v0
	v_mov_b32_e32 v122, v0
	v_mov_b32_e32 v123, v0
	v_mov_b32_e32 v124, v0
	v_mov_b32_e32 v125, v0
	v_mov_b32_e32 v126, v0
	v_mov_b32_e32 v127, v0
	v_mov_b32_e32 v136, v0
	v_mov_b32_e32 v137, v0
	v_mov_b32_e32 v138, v0
	v_mov_b32_e32 v139, v0
	v_mov_b32_e32 v140, v0
	v_mov_b32_e32 v141, v0
	v_mov_b32_e32 v142, v0
	v_mov_b32_e32 v143, v0
	v_mov_b32_e32 v152, v0
	v_mov_b32_e32 v153, v0
	v_mov_b32_e32 v154, v0
	v_mov_b32_e32 v155, v0
	v_mov_b32_e32 v156, v0
	v_mov_b32_e32 v157, v0
	v_mov_b32_e32 v158, v0
	v_mov_b32_e32 v159, v0
	v_mov_b32_e32 v168, v0
	v_mov_b32_e32 v169, v0
	v_mov_b32_e32 v170, v0
	v_mov_b32_e32 v171, v0
	v_mov_b32_e32 v172, v0
	v_mov_b32_e32 v173, v0
	v_mov_b32_e32 v174, v0
	v_mov_b32_e32 v175, v0
	v_readlane_b32 s98, v255, 13
	s_nop 4
	s_cmp_gt_u32 s98, 3
	s_cbranch_scc1 .Lprio_skip_353
	s_setprio 1

; #define PG8_BAR __builtin_amdgcn_s_barrier()
; template <class Sched, class Epi, bool ALIGN_EPI, bool SP2>
; __device__ __forceinline__ void gemm_phase(LAS unsigned char* lds, const int K, const int lda, const int ldb, const Sched& S, const Epi& E) {
;     ...
;         for (int t = 0; t < nt; t += 2) {
;             const bool last = (t == nt - 2);
;             const char* a1 = cA + (size_t)(t + 1) * kstep;
;             const char* a2 = last ? nA : cA + (size_t)(t + 2) * kstep; const char* b2 = last ? nB : cB + (size_t)(t + 2) * kstep;
;             const char* a3 = a2 + kstep; const char* b3 = b2 + kstep;
;     ...
;         cur = nxt; cA = nA; cB = nB; ++ui;
;         if constexpr (ALIGN_EPI) { if (wr == 1) PG8_BAR; }
.LBB0_820:
	s_add_u32 s53, s20, 0x100
	s_addc_u32 s60, s21, 0
	s_mov_b32 s61, -2
	v_readlane_b32 s98, v255, 13
	s_nop 4
	s_cmp_gt_u32 s98, 3
	s_cbranch_scc1 .Lprio_skip_821
	s_setprio 1

; #define PG8_BAR __builtin_amdgcn_s_barrier()
; template <class Sched, class Epi, bool ALIGN_EPI, bool SP2>
; __device__ __forceinline__ void gemm_phase(LAS unsigned char* lds, const int K, const int lda, const int ldb, const Sched& S, const Epi& E) {
;     ...
;     for (;;) {
;         const bool has_next = S.next(ui + 1, nxt);
;         const char* nA = has_next ? nxt.A : cA; const char* nB = has_next ? nxt.B : cB;
;         for (int t = 0; t < nt; t += 2) {
;     ...
;         if (!keep) {
; #pragma unroll
;         for (int a = 0; a < 2; ++a)
; #pragma unroll
;             for (int b = 0; b < 2; ++b)
; #pragma unroll
;                 for (int m = 0; m < 4; ++m)
; #pragma unroll
;                     for (int n = 0; n < 2; ++n) acc[a][b][m][n] = (f32x4){0.f, 0.f, 0.f, 0.f};
;         }
;         cur = nxt; cA = nA; cB = nB; ++ui;
;         if constexpr (ALIGN_EPI) { if (wr == 1) PG8_BAR; }
.LBB0_944:
	s_add_u32 s36, s36, 0x80080
	s_addc_u32 s37, s37, 0
	s_add_u32 s1, s42, 0x100
	v_mov_b32_e32 v0, 0
	s_addc_u32 s25, s43, 0
	s_mov_b32 s61, -2
	v_mov_b32_e32 v1, v0
	s_waitcnt lgkmcnt(0)
	v_mov_b32_e32 v2, v0
	v_mov_b32_e32 v3, v0
	v_mov_b32_e32 v4, v0
	v_mov_b32_e32 v5, v0
	v_mov_b32_e32 v6, v0
	v_mov_b32_e32 v7, v0
	v_mov_b32_e32 v16, v0
	v_mov_b32_e32 v17, v0
	v_mov_b32_e32 v18, v0
	v_mov_b32_e32 v19, v0
	v_mov_b32_e32 v20, v0
	v_mov_b32_e32 v21, v0
	v_mov_b32_e32 v22, v0
	v_mov_b32_e32 v23, v0
	v_mov_b32_e32 v32, v0
	v_mov_b32_e32 v33, v0
	v_mov_b32_e32 v34, v0
	v_mov_b32_e32 v35, v0
	v_mov_b32_e32 v36, v0
	v_mov_b32_e32 v37, v0
	v_mov_b32_e32 v38, v0
	v_mov_b32_e32 v39, v0
	v_mov_b32_e32 v48, v0
	v_mov_b32_e32 v49, v0
	v_mov_b32_e32 v50, v0
	v_mov_b32_e32 v51, v0
	v_mov_b32_e32 v60, v0
	v_mov_b32_e32 v61, v0
	v_mov_b32_e32 v62, v0
	v_mov_b32_e32 v63, v0
	v_mov_b32_e32 v8, v0
	v_mov_b32_e32 v9, v0
	v_mov_b32_e32 v10, v0
	v_mov_b32_e32 v11, v0
	v_mov_b32_e32 v12, v0
	v_mov_b32_e32 v13, v0
	v_mov_b32_e32 v14, v0
	v_mov_b32_e32 v15, v0
	v_mov_b32_e32 v24, v0
	v_mov_b32_e32 v25, v0
	v_mov_b32_e32 v26, v0
	v_mov_b32_e32 v27, v0
	v_mov_b32_e32 v28, v0
	v_mov_b32_e32 v29, v0
	v_mov_b32_e32 v30, v0
	v_mov_b32_e32 v31, v0
	v_mov_b32_e32 v40, v0
	v_mov_b32_e32 v41, v0
	v_mov_b32_e32 v42, v0
	v_mov_b32_e32 v43, v0
	v_mov_b32_e32 v44, v0
	v_mov_b32_e32 v45, v0
	v_mov_b32_e32 v46, v0
	v_mov_b32_e32 v47, v0
	v_mov_b32_e32 v80, v0
	v_mov_b32_e32 v81, v0
	v_mov_b32_e32 v82, v0
	v_mov_b32_e32 v83, v0
	v_mov_b32_e32 v84, v0
	v_mov_b32_e32 v85, v0
	v_mov_b32_e32 v86, v0
	v_mov_b32_e32 v87, v0
	v_mov_b32_e32 v96, v0
	v_mov_b32_e32 v97, v0
	v_mov_b32_e32 v98, v0
	v_mov_b32_e32 v99, v0
	v_mov_b32_e32 v100, v0
	v_mov_b32_e32 v101, v0
	v_mov_b32_e32 v102, v0
	v_mov_b32_e32 v103, v0
	v_mov_b32_e32 v112, v0
	v_mov_b32_e32 v113, v0
	v_mov_b32_e32 v114, v0
	v_mov_b32_e32 v115, v0
	v_mov_b32_e32 v116, v0
	v_mov_b32_e32 v117, v0
	v_mov_b32_e32 v118, v0
	v_mov_b32_e32 v119, v0
	v_mov_b32_e32 v128, v0
	v_mov_b32_e32 v129, v0
	v_mov_b32_e32 v130, v0
	v_mov_b32_e32 v131, v0
	v_mov_b32_e32 v132, v0
	v_mov_b32_e32 v133, v0
	v_mov_b32_e32 v134, v0
	v_mov_b32_e32 v135, v0
	v_mov_b32_e32 v144, v0
	v_mov_b32_e32 v145, v0
	v_mov_b32_e32 v146, v0
	v_mov_b32_e32 v147, v0
	v_mov_b32_e32 v148, v0
	v_mov_b32_e32 v149, v0
	v_mov_b32_e32 v150, v0
	v_mov_b32_e32 v151, v0
	v_mov_b32_e32 v104, v0
	v_mov_b32_e32 v105, v0
	v_mov_b32_e32 v106, v0
	v_mov_b32_e32 v107, v0
	v_mov_b32_e32 v108, v0
	v_mov_b32_e32 v109, v0
	v_mov_b32_e32 v110, v0
	v_mov_b32_e32 v111, v0
	v_mov_b32_e32 v120, v0
	v_mov_b32_e32 v121, v0
	v_mov_b32_e32 v122, v0
	v_mov_b32_e32 v123, v0
	v_mov_b32_e32 v124, v0
	v_mov_b32_e32 v125, v0
	v_mov_b32_e32 v126, v0
	v_mov_b32_e32 v127, v0
	v_mov_b32_e32 v136, v0
	v_mov_b32_e32 v137, v0
	v_mov_b32_e32 v138, v0
	v_mov_b32_e32 v139, v0
	v_mov_b32_e32 v140, v0
	v_mov_b32_e32 v141, v0
	v_mov_b32_e32 v142, v0
	v_mov_b32_e32 v143, v0
	v_mov_b32_e32 v152, v0
	v_mov_b32_e32 v153, v0
	v_mov_b32_e32 v154, v0
	v_mov_b32_e32 v155, v0
	v_mov_b32_e32 v156, v0
	v_mov_b32_e32 v157, v0
	v_mov_b32_e32 v158, v0
	v_mov_b32_e32 v159, v0
	v_readlane_b32 s98, v255, 13
	s_nop 4
	s_cmp_gt_u32 s98, 3
	s_cbranch_scc1 .Lprio_skip_945
	s_setprio 1

; #define PG8_BAR __builtin_amdgcn_s_barrier()
; template <class Sched, class Epi, bool ALIGN_EPI, bool SP2>
; __device__ __forceinline__ void gemm_phase(LAS unsigned char* lds, const int K, const int lda, const int ldb, const Sched& S, const Epi& E) {
;     ...
;     for (;;) {
;         const bool has_next = S.next(ui + 1, nxt);
;         const char* nA = has_next ? nxt.A : cA; const char* nB = has_next ? nxt.B : cB;
;         for (int t = 0; t < nt; t += 2) {
;     ...
;         if (!keep) {
; #pragma unroll
;         for (int a = 0; a < 2; ++a)
; #pragma unroll
;             for (int b = 0; b < 2; ++b)
; #pragma unroll
;                 for (int m = 0; m < 4; ++m)
; #pragma unroll
;                     for (int n = 0; n < 2; ++n) acc[a][b][m][n] = (f32x4){0.f, 0.f, 0.f, 0.f};
;         }
;         cur = nxt; cA = nA; cB = nB; ++ui;
;         if constexpr (ALIGN_EPI) { if (wr == 1) PG8_BAR; }
.LBB0_1036:
	s_add_u32 s36, s36, 0x80080
	s_addc_u32 s37, s37, 0
	s_add_u32 s25, s42, 0x100
	v_mov_b32_e32 v4, 0
	s_addc_u32 s56, s43, 0
	s_mov_b32 s57, -2
	v_mov_b32_e32 v5, v4
	v_mov_b32_e32 v6, v4
	v_mov_b32_e32 v7, v4
	v_mov_b32_e32 v12, v4
	v_mov_b32_e32 v13, v4
	v_mov_b32_e32 v14, v4
	v_mov_b32_e32 v15, v4
	v_mov_b32_e32 v16, v4
	v_mov_b32_e32 v17, v4
	v_mov_b32_e32 v18, v4
	v_mov_b32_e32 v19, v4
	v_mov_b32_e32 v28, v4
	v_mov_b32_e32 v29, v4
	v_mov_b32_e32 v30, v4
	v_mov_b32_e32 v31, v4
	v_mov_b32_e32 v32, v4
	v_mov_b32_e32 v33, v4
	v_mov_b32_e32 v34, v4
	v_mov_b32_e32 v35, v4
	v_mov_b32_e32 v36, v4
	v_mov_b32_e32 v37, v4
	v_mov_b32_e32 v38, v4
	v_mov_b32_e32 v39, v4
	v_mov_b32_e32 v48, v4
	v_mov_b32_e32 v49, v4
	v_mov_b32_e32 v50, v4
	v_mov_b32_e32 v51, v4
	v_mov_b32_e32 v52, v4
	v_mov_b32_e32 v53, v4
	v_mov_b32_e32 v54, v4
	v_mov_b32_e32 v55, v4
	v_mov_b32_e32 v0, v4
	v_mov_b32_e32 v1, v4
	v_mov_b32_e32 v2, v4
	v_mov_b32_e32 v3, v4
	v_mov_b32_e32 v8, v4
	v_mov_b32_e32 v9, v4
	v_mov_b32_e32 v10, v4
	v_mov_b32_e32 v11, v4
	v_mov_b32_e32 v20, v4
	v_mov_b32_e32 v21, v4
	v_mov_b32_e32 v22, v4
	v_mov_b32_e32 v23, v4
	v_mov_b32_e32 v24, v4
	v_mov_b32_e32 v25, v4
	v_mov_b32_e32 v26, v4
	v_mov_b32_e32 v27, v4
	v_mov_b32_e32 v40, v4
	v_mov_b32_e32 v41, v4
	v_mov_b32_e32 v42, v4
	v_mov_b32_e32 v43, v4
	v_mov_b32_e32 v44, v4
	v_mov_b32_e32 v45, v4
	v_mov_b32_e32 v46, v4
	v_mov_b32_e32 v47, v4
	v_mov_b32_e32 v56, v4
	v_mov_b32_e32 v57, v4
	v_mov_b32_e32 v58, v4
	v_mov_b32_e32 v59, v4
	v_mov_b32_e32 v60, v4
	v_mov_b32_e32 v61, v4
	v_mov_b32_e32 v62, v4
	v_mov_b32_e32 v63, v4
	v_mov_b32_e32 v80, v4
	v_mov_b32_e32 v81, v4
	v_mov_b32_e32 v82, v4
	v_mov_b32_e32 v83, v4
	v_mov_b32_e32 v84, v4
	v_mov_b32_e32 v85, v4
	v_mov_b32_e32 v86, v4
	v_mov_b32_e32 v87, v4
	v_mov_b32_e32 v96, v4
	v_mov_b32_e32 v97, v4
	v_mov_b32_e32 v98, v4
	v_mov_b32_e32 v99, v4
	v_mov_b32_e32 v100, v4
	v_mov_b32_e32 v101, v4
	v_mov_b32_e32 v102, v4
	v_mov_b32_e32 v103, v4
	v_mov_b32_e32 v112, v4
	v_mov_b32_e32 v113, v4
	v_mov_b32_e32 v114, v4
	v_mov_b32_e32 v115, v4
	v_mov_b32_e32 v116, v4
	v_mov_b32_e32 v117, v4
	v_mov_b32_e32 v118, v4
	v_mov_b32_e32 v119, v4
	v_mov_b32_e32 v128, v4
	v_mov_b32_e32 v129, v4
	v_mov_b32_e32 v130, v4
	v_mov_b32_e32 v131, v4
	v_mov_b32_e32 v132, v4
	v_mov_b32_e32 v133, v4
	v_mov_b32_e32 v134, v4
	v_mov_b32_e32 v135, v4
	v_mov_b32_e32 v88, v4
	v_mov_b32_e32 v89, v4
	v_mov_b32_e32 v90, v4
	v_mov_b32_e32 v91, v4
	v_mov_b32_e32 v92, v4
	v_mov_b32_e32 v93, v4
	v_mov_b32_e32 v94, v4
	v_mov_b32_e32 v95, v4
	v_mov_b32_e32 v104, v4
	v_mov_b32_e32 v105, v4
	v_mov_b32_e32 v106, v4
	v_mov_b32_e32 v107, v4
	v_mov_b32_e32 v108, v4
	v_mov_b32_e32 v109, v4
	v_mov_b32_e32 v110, v4
	v_mov_b32_e32 v111, v4
	v_mov_b32_e32 v120, v4
	v_mov_b32_e32 v121, v4
	v_mov_b32_e32 v122, v4
	v_mov_b32_e32 v123, v4
	v_mov_b32_e32 v124, v4
	v_mov_b32_e32 v125, v4
	v_mov_b32_e32 v126, v4
	v_mov_b32_e32 v127, v4
	v_mov_b32_e32 v136, v4
	v_mov_b32_e32 v137, v4
	v_mov_b32_e32 v138, v4
	v_mov_b32_e32 v139, v4
	v_mov_b32_e32 v140, v4
	v_mov_b32_e32 v141, v4
	v_mov_b32_e32 v142, v4
	v_mov_b32_e32 v143, v4
	v_readlane_b32 s98, v255, 13
	s_nop 4
	s_cmp_gt_u32 s98, 3
	s_cbranch_scc1 .Lprio_skip_1037
	s_setprio 1

; #define PG8_BAR __builtin_amdgcn_s_barrier()
; template <class Sched, class Epi, bool ALIGN_EPI, bool SP2>
; __device__ __forceinline__ void gemm_phase(LAS unsigned char* lds, const int K, const int lda, const int ldb, const Sched& S, const Epi& E) {
;     ...
;     for (;;) {
;         const bool has_next = S.next(ui + 1, nxt);
;         const char* nA = has_next ? nxt.A : cA; const char* nB = has_next ? nxt.B : cB;
;         for (int t = 0; t < nt; t += 2) {
;     ...
;         if (!keep) {
; #pragma unroll
;         for (int a = 0; a < 2; ++a)
; #pragma unroll
;             for (int b = 0; b < 2; ++b)
; #pragma unroll
;                 for (int m = 0; m < 4; ++m)
; #pragma unroll
;                     for (int n = 0; n < 2; ++n) acc[a][b][m][n] = (f32x4){0.f, 0.f, 0.f, 0.f};
;         }
;         cur = nxt; cA = nA; cB = nB; ++ui;
;         if constexpr (ALIGN_EPI) { if (wr == 1) PG8_BAR; }
.LBB0_1119:
	s_add_u32 s49, s4, 0x100
	v_mov_b32_e32 v0, 0
	s_addc_u32 s50, s5, 0
	s_mov_b32 s51, -2
	v_mov_b32_e32 v1, v0
	v_mov_b32_e32 v2, v0
	v_mov_b32_e32 v3, v0
	v_mov_b32_e32 v4, v0
	v_mov_b32_e32 v5, v0
	v_mov_b32_e32 v6, v0
	v_mov_b32_e32 v7, v0
	v_mov_b32_e32 v12, v0
	v_mov_b32_e32 v13, v0
	v_mov_b32_e32 v14, v0
	v_mov_b32_e32 v15, v0
	v_mov_b32_e32 v20, v0
	v_mov_b32_e32 v21, v0
	v_mov_b32_e32 v22, v0
	v_mov_b32_e32 v23, v0
	v_mov_b32_e32 v32, v0
	v_mov_b32_e32 v33, v0
	v_mov_b32_e32 v34, v0
	v_mov_b32_e32 v35, v0
	v_mov_b32_e32 v36, v0
	v_mov_b32_e32 v37, v0
	v_mov_b32_e32 v38, v0
	v_mov_b32_e32 v39, v0
	v_mov_b32_e32 v44, v0
	v_mov_b32_e32 v45, v0
	v_mov_b32_e32 v46, v0
	v_mov_b32_e32 v47, v0
	v_mov_b32_e32 v52, v0
	v_mov_b32_e32 v53, v0
	v_mov_b32_e32 v54, v0
	v_mov_b32_e32 v55, v0
	v_mov_b32_e32 v8, v0
	v_mov_b32_e32 v9, v0
	v_mov_b32_e32 v10, v0
	v_mov_b32_e32 v11, v0
	v_mov_b32_e32 v16, v0
	v_mov_b32_e32 v17, v0
	v_mov_b32_e32 v18, v0
	v_mov_b32_e32 v19, v0
	v_mov_b32_e32 v24, v0
	v_mov_b32_e32 v25, v0
	v_mov_b32_e32 v26, v0
	v_mov_b32_e32 v27, v0
	v_mov_b32_e32 v28, v0
	v_mov_b32_e32 v29, v0
	v_mov_b32_e32 v30, v0
	v_mov_b32_e32 v31, v0
	v_mov_b32_e32 v40, v0
	v_mov_b32_e32 v41, v0
	v_mov_b32_e32 v42, v0
	v_mov_b32_e32 v43, v0
	v_mov_b32_e32 v48, v0
	v_mov_b32_e32 v49, v0
	v_mov_b32_e32 v50, v0
	v_mov_b32_e32 v51, v0
	v_mov_b32_e32 v56, v0
	v_mov_b32_e32 v57, v0
	v_mov_b32_e32 v58, v0
	v_mov_b32_e32 v59, v0
	v_mov_b32_e32 v60, v0
	v_mov_b32_e32 v61, v0
	v_mov_b32_e32 v62, v0
	v_mov_b32_e32 v63, v0
	v_mov_b32_e32 v64, v0
	v_mov_b32_e32 v65, v0
	v_mov_b32_e32 v66, v0
	v_mov_b32_e32 v67, v0
	v_mov_b32_e32 v68, v0
	v_mov_b32_e32 v69, v0
	v_mov_b32_e32 v70, v0
	v_mov_b32_e32 v71, v0
	v_mov_b32_e32 v76, v0
	v_mov_b32_e32 v77, v0
	v_mov_b32_e32 v78, v0
	v_mov_b32_e32 v79, v0
	v_mov_b32_e32 v84, v0
	v_mov_b32_e32 v85, v0
	v_mov_b32_e32 v86, v0
	v_mov_b32_e32 v87, v0
	v_mov_b32_e32 v128, v0
	v_mov_b32_e32 v129, v0
	v_mov_b32_e32 v130, v0
	v_mov_b32_e32 v131, v0
	v_mov_b32_e32 v132, v0
	v_mov_b32_e32 v133, v0
	v_mov_b32_e32 v134, v0
	v_mov_b32_e32 v135, v0
	v_mov_b32_e32 v140, v0
	v_mov_b32_e32 v141, v0
	v_mov_b32_e32 v142, v0
	v_mov_b32_e32 v143, v0
	v_mov_b32_e32 v148, v0
	v_mov_b32_e32 v149, v0
	v_mov_b32_e32 v150, v0
	v_mov_b32_e32 v151, v0
	v_mov_b32_e32 v72, v0
	v_mov_b32_e32 v73, v0
	v_mov_b32_e32 v74, v0
	v_mov_b32_e32 v75, v0
	v_mov_b32_e32 v80, v0
	v_mov_b32_e32 v81, v0
	v_mov_b32_e32 v82, v0
	v_mov_b32_e32 v83, v0
	v_mov_b32_e32 v88, v0
	v_mov_b32_e32 v89, v0
	v_mov_b32_e32 v90, v0
	v_mov_b32_e32 v91, v0
	v_mov_b32_e32 v92, v0
	v_mov_b32_e32 v93, v0
	v_mov_b32_e32 v94, v0
	v_mov_b32_e32 v95, v0
	v_mov_b32_e32 v136, v0
	v_mov_b32_e32 v137, v0
	v_mov_b32_e32 v138, v0
	v_mov_b32_e32 v139, v0
	v_mov_b32_e32 v144, v0
	v_mov_b32_e32 v145, v0
	v_mov_b32_e32 v146, v0
	v_mov_b32_e32 v147, v0
	v_mov_b32_e32 v152, v0
	v_mov_b32_e32 v153, v0
	v_mov_b32_e32 v154, v0
	v_mov_b32_e32 v155, v0
	v_mov_b32_e32 v156, v0
	v_mov_b32_e32 v157, v0
	v_mov_b32_e32 v158, v0
	v_mov_b32_e32 v159, v0
	v_readlane_b32 s98, v255, 13
	s_nop 4
	s_cmp_gt_u32 s98, 3
	s_cbranch_scc1 .Lprio_skip_1120
	s_setprio 1
